# non-temporal hint on the once-read streams of the scan phase: p_cvec w_ff1 loads and the loaders' record loads
# speedup vs baseline: 1.0063x; 1.0063x over previous
.LBB0_494:
	v_lshl_add_u64 v[12:13], v[2:3], 0, s[0:1]
	v_add_co_u32_e32 v144, vcc, s6, v12
	global_load_dword v142, v[12:13], off nt
	s_nop 0
	v_addc_co_u32_e32 v145, vcc, 0, v13, vcc
	v_add_co_u32_e32 v146, vcc, s7, v12
	v_mov_b32_e32 v138, s3
	s_nop 0
	v_addc_co_u32_e32 v147, vcc, 0, v13, vcc
	v_add_co_u32_e32 v148, vcc, s8, v12
	ds_read_b128 v[14:17], v138
	ds_read_b128 v[18:21], v138 offset:16
	ds_read_b128 v[22:25], v138 offset:32
	ds_read_b128 v[26:29], v138 offset:48
	v_addc_co_u32_e32 v149, vcc, 0, v13, vcc
	v_add_co_u32_e32 v150, vcc, s9, v12
	ds_read_b128 v[30:33], v138 offset:4096
	ds_read_b128 v[34:37], v138 offset:4112
	ds_read_b128 v[38:41], v138 offset:8192
	ds_read_b128 v[42:45], v138 offset:8208
	ds_read_b128 v[46:49], v138 offset:12288
	ds_read_b128 v[50:53], v138 offset:12304
	ds_read_b128 v[54:57], v138 offset:16384
	ds_read_b128 v[58:61], v138 offset:16400
	ds_read_b128 v[62:65], v138 offset:20480
	ds_read_b128 v[66:69], v138 offset:20496
	ds_read_b128 v[70:73], v138 offset:24576
	ds_read_b128 v[74:77], v138 offset:24592
	ds_read_b128 v[78:81], v138 offset:28672
	ds_read_b128 v[82:85], v138 offset:28688
	v_addc_co_u32_e32 v151, vcc, 0, v13, vcc
	v_add_co_u32_e32 v152, vcc, s12, v12
	ds_read_b128 v[86:89], v138 offset:4128
	ds_read_b128 v[90:93], v138 offset:4144
	ds_read_b128 v[94:97], v138 offset:8224
	ds_read_b128 v[98:101], v138 offset:8240
	ds_read_b128 v[102:105], v138 offset:12320
	ds_read_b128 v[106:109], v138 offset:12336
	ds_read_b128 v[110:113], v138 offset:16416
	ds_read_b128 v[114:117], v138 offset:16432
	ds_read_b128 v[118:121], v138 offset:20512
	ds_read_b128 v[122:125], v138 offset:20528
	ds_read_b128 v[126:129], v138 offset:24608
	ds_read_b128 v[130:133], v138 offset:24624
	ds_read_b128 v[134:137], v138 offset:28704
	ds_read_b128 v[138:141], v138 offset:28720
	v_addc_co_u32_e32 v153, vcc, 0, v13, vcc
	v_add_co_u32_e32 v154, vcc, s13, v12
	s_waitcnt lgkmcnt(14)
	v_mov_b32_e32 v172, v14
	v_addc_co_u32_e32 v155, vcc, 0, v13, vcc
	v_add_co_u32_e32 v156, vcc, s14, v12
	v_mov_b32_e32 v173, v30
	s_nop 0
	v_addc_co_u32_e32 v157, vcc, 0, v13, vcc
	v_add_co_u32_e32 v158, vcc, s15, v12
	v_mov_b32_e32 v174, v38
	s_nop 0
	v_addc_co_u32_e32 v159, vcc, 0, v13, vcc
	v_add_co_u32_e32 v160, vcc, s16, v12
	v_mov_b32_e32 v175, v46
	s_nop 0
	v_addc_co_u32_e32 v161, vcc, 0, v13, vcc
	v_add_co_u32_e32 v162, vcc, s17, v12
	v_mov_b32_e32 v176, v54
	s_nop 0
	v_addc_co_u32_e32 v163, vcc, 0, v13, vcc
	v_add_co_u32_e32 v164, vcc, s26, v12
	v_mov_b32_e32 v177, v62
	s_nop 0
	v_addc_co_u32_e32 v165, vcc, 0, v13, vcc
	v_add_co_u32_e32 v166, vcc, s27, v12
	v_mov_b32_e32 v178, v70
	s_nop 0
	v_addc_co_u32_e32 v167, vcc, 0, v13, vcc
	v_add_co_u32_e32 v168, vcc, s28, v12
	v_mov_b32_e32 v179, v78
	s_nop 0
	v_addc_co_u32_e32 v169, vcc, 0, v13, vcc
	v_add_co_u32_e32 v170, vcc, s29, v12
	v_mov_b32_e32 v30, v15
	s_nop 0
	v_addc_co_u32_e32 v171, vcc, 0, v13, vcc
	v_add_co_u32_e32 v12, vcc, s34, v12
	v_mov_b32_e32 v46, v39
	s_nop 0
	v_addc_co_u32_e32 v13, vcc, 0, v13, vcc
	global_load_dword v144, v[144:145], off nt
	s_nop 0
	global_load_dword v146, v[146:147], off nt
	s_nop 0
	global_load_dword v148, v[148:149], off nt
	s_nop 0
	global_load_dword v150, v[150:151], off nt
	s_nop 0
	global_load_dword v152, v[152:153], off nt
	s_nop 0
	global_load_dword v154, v[154:155], off nt
	s_nop 0
	global_load_dword v156, v[156:157], off nt
	s_nop 0
	global_load_dword v158, v[158:159], off nt
	s_nop 0
	global_load_dword v160, v[160:161], off nt
	s_nop 0
	global_load_dword v162, v[162:163], off nt
	s_nop 0
	global_load_dword v164, v[164:165], off nt
	s_nop 0
	global_load_dword v166, v[166:167], off nt
	s_nop 0
	global_load_dword v168, v[168:169], off nt
	s_nop 0
	global_load_dword v170, v[170:171], off nt
	s_nop 0
	global_load_dword v12, v[12:13], off nt
	v_mov_b32_e32 v62, v55
	v_mov_b32_e32 v78, v71
	v_mov_b32_e32 v14, v16
	v_mov_b32_e32 v15, v32
	v_mov_b32_e32 v38, v40
	v_mov_b32_e32 v39, v48
	s_waitcnt vmcnt(15)
	v_pk_fma_f32 v[10:11], v[142:143], v[172:173], v[10:11] op_sel_hi:[0,1,1]
	v_pk_fma_f32 v[8:9], v[142:143], v[174:175], v[8:9] op_sel_hi:[0,1,1]
	v_pk_fma_f32 v[6:7], v[142:143], v[176:177], v[6:7] op_sel_hi:[0,1,1]
	v_pk_fma_f32 v[4:5], v[142:143], v[178:179], v[4:5] op_sel_hi:[0,1,1]
	v_mov_b32_e32 v54, v56
	v_mov_b32_e32 v55, v64
	v_mov_b32_e32 v70, v72
	v_mov_b32_e32 v71, v80
	v_mov_b32_e32 v32, v17
	v_mov_b32_e32 v48, v41
	v_mov_b32_e32 v64, v57
	v_mov_b32_e32 v80, v73
	v_mov_b32_e32 v16, v18
	v_mov_b32_e32 v17, v34
	v_mov_b32_e32 v40, v42
	v_mov_b32_e32 v41, v50
	v_mov_b32_e32 v56, v58
	v_mov_b32_e32 v57, v66
	v_mov_b32_e32 v72, v74
	v_mov_b32_e32 v73, v82
	v_mov_b32_e32 v34, v19
	v_mov_b32_e32 v50, v43
	v_mov_b32_e32 v66, v59
	v_mov_b32_e32 v82, v75
	v_mov_b32_e32 v18, v20
	v_mov_b32_e32 v19, v36
	v_mov_b32_e32 v42, v44
	v_mov_b32_e32 v43, v52
	v_mov_b32_e32 v58, v60
	v_mov_b32_e32 v59, v68
	v_mov_b32_e32 v74, v76
	v_mov_b32_e32 v75, v84
	v_mov_b32_e32 v36, v21
	v_mov_b32_e32 v52, v45
	v_mov_b32_e32 v68, v61
	v_mov_b32_e32 v84, v77
	v_mov_b32_e32 v20, v22
	s_waitcnt lgkmcnt(13)
	v_mov_b32_e32 v21, v86
	s_waitcnt lgkmcnt(11)
	v_mov_b32_e32 v44, v94
	s_waitcnt lgkmcnt(9)
	v_mov_b32_e32 v45, v102
	s_waitcnt lgkmcnt(7)
	v_mov_b32_e32 v60, v110
	s_waitcnt lgkmcnt(5)
	v_mov_b32_e32 v61, v118
	s_waitcnt lgkmcnt(3)
	v_mov_b32_e32 v76, v126
	s_waitcnt lgkmcnt(1)
	v_mov_b32_e32 v77, v134
	v_mov_b32_e32 v86, v23
	v_mov_b32_e32 v102, v95
	v_mov_b32_e32 v118, v111
	v_mov_b32_e32 v134, v127
	v_mov_b32_e32 v22, v24
	v_mov_b32_e32 v23, v88
	v_mov_b32_e32 v94, v96
	v_mov_b32_e32 v95, v104
	v_mov_b32_e32 v110, v112
	v_mov_b32_e32 v111, v120
	v_mov_b32_e32 v126, v128
	v_mov_b32_e32 v127, v136
	v_mov_b32_e32 v88, v25
	v_mov_b32_e32 v104, v97
	v_mov_b32_e32 v120, v113
	s_waitcnt vmcnt(14)
	v_pk_fma_f32 v[10:11], v[144:145], v[30:31], v[10:11] op_sel_hi:[0,1,1]
	v_pk_fma_f32 v[8:9], v[144:145], v[46:47], v[8:9] op_sel_hi:[0,1,1]
	v_pk_fma_f32 v[6:7], v[144:145], v[62:63], v[6:7] op_sel_hi:[0,1,1]
	v_pk_fma_f32 v[4:5], v[144:145], v[78:79], v[4:5] op_sel_hi:[0,1,1]
	s_waitcnt vmcnt(13)
	v_pk_fma_f32 v[10:11], v[146:147], v[14:15], v[10:11] op_sel_hi:[0,1,1]
	v_pk_fma_f32 v[8:9], v[146:147], v[38:39], v[8:9] op_sel_hi:[0,1,1]
	v_pk_fma_f32 v[6:7], v[146:147], v[54:55], v[6:7] op_sel_hi:[0,1,1]
	v_pk_fma_f32 v[4:5], v[146:147], v[70:71], v[4:5] op_sel_hi:[0,1,1]
	s_waitcnt vmcnt(12)
	v_pk_fma_f32 v[10:11], v[148:149], v[32:33], v[10:11] op_sel_hi:[0,1,1]
	v_pk_fma_f32 v[8:9], v[148:149], v[48:49], v[8:9] op_sel_hi:[0,1,1]
	v_pk_fma_f32 v[6:7], v[148:149], v[64:65], v[6:7] op_sel_hi:[0,1,1]
	v_pk_fma_f32 v[4:5], v[148:149], v[80:81], v[4:5] op_sel_hi:[0,1,1]
	s_waitcnt vmcnt(11)
	v_pk_fma_f32 v[10:11], v[150:151], v[16:17], v[10:11] op_sel_hi:[0,1,1]
	v_pk_fma_f32 v[8:9], v[150:151], v[40:41], v[8:9] op_sel_hi:[0,1,1]
	v_pk_fma_f32 v[6:7], v[150:151], v[56:57], v[6:7] op_sel_hi:[0,1,1]
	v_pk_fma_f32 v[4:5], v[150:151], v[72:73], v[4:5] op_sel_hi:[0,1,1]
	s_waitcnt vmcnt(10)
	v_pk_fma_f32 v[10:11], v[152:153], v[34:35], v[10:11] op_sel_hi:[0,1,1]
	v_pk_fma_f32 v[8:9], v[152:153], v[50:51], v[8:9] op_sel_hi:[0,1,1]
	v_pk_fma_f32 v[6:7], v[152:153], v[66:67], v[6:7] op_sel_hi:[0,1,1]
	v_pk_fma_f32 v[4:5], v[152:153], v[82:83], v[4:5] op_sel_hi:[0,1,1]
	s_waitcnt vmcnt(9)
	v_pk_fma_f32 v[10:11], v[154:155], v[18:19], v[10:11] op_sel_hi:[0,1,1]
	v_pk_fma_f32 v[8:9], v[154:155], v[42:43], v[8:9] op_sel_hi:[0,1,1]
	v_pk_fma_f32 v[6:7], v[154:155], v[58:59], v[6:7] op_sel_hi:[0,1,1]
	v_pk_fma_f32 v[4:5], v[154:155], v[74:75], v[4:5] op_sel_hi:[0,1,1]
	s_waitcnt vmcnt(8)
	v_pk_fma_f32 v[10:11], v[156:157], v[36:37], v[10:11] op_sel_hi:[0,1,1]
	v_pk_fma_f32 v[8:9], v[156:157], v[52:53], v[8:9] op_sel_hi:[0,1,1]
	v_pk_fma_f32 v[6:7], v[156:157], v[68:69], v[6:7] op_sel_hi:[0,1,1]
	v_pk_fma_f32 v[4:5], v[156:157], v[84:85], v[4:5] op_sel_hi:[0,1,1]
	s_waitcnt vmcnt(7)
	v_pk_fma_f32 v[10:11], v[158:159], v[20:21], v[10:11] op_sel_hi:[0,1,1]
	v_pk_fma_f32 v[8:9], v[158:159], v[44:45], v[8:9] op_sel_hi:[0,1,1]
	v_pk_fma_f32 v[6:7], v[158:159], v[60:61], v[6:7] op_sel_hi:[0,1,1]
	v_pk_fma_f32 v[4:5], v[158:159], v[76:77], v[4:5] op_sel_hi:[0,1,1]
	s_waitcnt vmcnt(6)
	v_pk_fma_f32 v[10:11], v[160:161], v[86:87], v[10:11] op_sel_hi:[0,1,1]
	v_pk_fma_f32 v[8:9], v[160:161], v[102:103], v[8:9] op_sel_hi:[0,1,1]
	v_pk_fma_f32 v[6:7], v[160:161], v[118:119], v[6:7] op_sel_hi:[0,1,1]
	v_pk_fma_f32 v[4:5], v[160:161], v[134:135], v[4:5] op_sel_hi:[0,1,1]
	v_mov_b32_e32 v136, v129
	s_waitcnt vmcnt(5)
	v_pk_fma_f32 v[10:11], v[162:163], v[22:23], v[10:11] op_sel_hi:[0,1,1]
	v_pk_fma_f32 v[8:9], v[162:163], v[94:95], v[8:9] op_sel_hi:[0,1,1]
	v_pk_fma_f32 v[6:7], v[162:163], v[110:111], v[6:7] op_sel_hi:[0,1,1]
	v_pk_fma_f32 v[4:5], v[162:163], v[126:127], v[4:5] op_sel_hi:[0,1,1]
	v_mov_b32_e32 v24, v26
	v_mov_b32_e32 v25, v90
	v_mov_b32_e32 v96, v98
	v_mov_b32_e32 v97, v106
	v_mov_b32_e32 v112, v114
	v_mov_b32_e32 v113, v122
	v_mov_b32_e32 v128, v130
	s_waitcnt lgkmcnt(0)
	v_mov_b32_e32 v129, v138
	s_waitcnt vmcnt(4)
	v_pk_fma_f32 v[10:11], v[164:165], v[88:89], v[10:11] op_sel_hi:[0,1,1]
	v_pk_fma_f32 v[8:9], v[164:165], v[104:105], v[8:9] op_sel_hi:[0,1,1]
	v_pk_fma_f32 v[6:7], v[164:165], v[120:121], v[6:7] op_sel_hi:[0,1,1]
	v_pk_fma_f32 v[4:5], v[164:165], v[136:137], v[4:5] op_sel_hi:[0,1,1]
	v_mov_b32_e32 v90, v27
	v_mov_b32_e32 v106, v99
	v_mov_b32_e32 v122, v115
	v_mov_b32_e32 v138, v131
	s_waitcnt vmcnt(3)
	v_pk_fma_f32 v[10:11], v[166:167], v[24:25], v[10:11] op_sel_hi:[0,1,1]
	v_pk_fma_f32 v[8:9], v[166:167], v[96:97], v[8:9] op_sel_hi:[0,1,1]
	v_pk_fma_f32 v[6:7], v[166:167], v[112:113], v[6:7] op_sel_hi:[0,1,1]
	v_pk_fma_f32 v[4:5], v[166:167], v[128:129], v[4:5] op_sel_hi:[0,1,1]
	s_add_u32 s0, s0, 0x40000
	v_mov_b32_e32 v26, v28
	v_mov_b32_e32 v27, v92
	v_mov_b32_e32 v98, v100
	v_mov_b32_e32 v99, v108
	v_mov_b32_e32 v114, v116
	v_mov_b32_e32 v115, v124
	v_mov_b32_e32 v130, v132
	v_mov_b32_e32 v131, v140
	s_waitcnt vmcnt(2)
	v_pk_fma_f32 v[10:11], v[168:169], v[90:91], v[10:11] op_sel_hi:[0,1,1]
	v_pk_fma_f32 v[8:9], v[168:169], v[106:107], v[8:9] op_sel_hi:[0,1,1]
	v_pk_fma_f32 v[6:7], v[168:169], v[122:123], v[6:7] op_sel_hi:[0,1,1]
	v_pk_fma_f32 v[4:5], v[168:169], v[138:139], v[4:5] op_sel_hi:[0,1,1]
	s_addc_u32 s1, s1, 0
	s_add_i32 s3, s3, 64
	v_mov_b32_e32 v92, v29
	v_mov_b32_e32 v108, v101
	v_mov_b32_e32 v124, v117
	v_mov_b32_e32 v140, v133
	s_waitcnt vmcnt(1)
	v_pk_fma_f32 v[10:11], v[170:171], v[26:27], v[10:11] op_sel_hi:[0,1,1]
	v_pk_fma_f32 v[8:9], v[170:171], v[98:99], v[8:9] op_sel_hi:[0,1,1]
	v_pk_fma_f32 v[6:7], v[170:171], v[114:115], v[6:7] op_sel_hi:[0,1,1]
	v_pk_fma_f32 v[4:5], v[170:171], v[130:131], v[4:5] op_sel_hi:[0,1,1]
	s_cmp_lg_u32 s0, 0x1000000
	s_waitcnt vmcnt(0)
	v_pk_fma_f32 v[10:11], v[12:13], v[92:93], v[10:11] op_sel_hi:[0,1,1]
	v_pk_fma_f32 v[8:9], v[12:13], v[108:109], v[8:9] op_sel_hi:[0,1,1]
	v_pk_fma_f32 v[6:7], v[12:13], v[124:125], v[6:7] op_sel_hi:[0,1,1]
	v_pk_fma_f32 v[4:5], v[12:13], v[140:141], v[4:5] op_sel_hi:[0,1,1]
	s_cbranch_scc1 .LBB0_494
	v_lshl_add_u64 v[0:1], v[0:1], 2, s[54:55]
	v_add_co_u32_e32 v2, vcc, 0x1a80000, v0
	s_nop 1
	v_addc_co_u32_e32 v3, vcc, 0, v1, vcc
	global_store_dword v[2:3], v10, off
	v_add_co_u32_e32 v2, vcc, 0x1a84000, v0
	s_nop 1
	v_addc_co_u32_e32 v3, vcc, 0, v1, vcc
	global_store_dword v[2:3], v11, off
	v_add_co_u32_e32 v2, vcc, 0x1a88000, v0
	s_nop 1
	v_addc_co_u32_e32 v3, vcc, 0, v1, vcc
	global_store_dword v[2:3], v8, off
	v_add_co_u32_e32 v2, vcc, 0x1a8c000, v0
	s_nop 1
	v_addc_co_u32_e32 v3, vcc, 0, v1, vcc
	global_store_dword v[2:3], v9, off
	v_add_co_u32_e32 v2, vcc, 0x1a90000, v0
	s_nop 1
	v_addc_co_u32_e32 v3, vcc, 0, v1, vcc
	global_store_dword v[2:3], v6, off
	v_add_co_u32_e32 v2, vcc, 0x1a94000, v0
	s_nop 1
	v_addc_co_u32_e32 v3, vcc, 0, v1, vcc
	global_store_dword v[2:3], v7, off
	v_add_co_u32_e32 v2, vcc, 0x1a98000, v0
	s_nop 1
	v_addc_co_u32_e32 v3, vcc, 0, v1, vcc
	v_add_co_u32_e32 v0, vcc, 0x1a9c000, v0
	global_store_dword v[2:3], v4, off
	s_nop 0
	v_addc_co_u32_e32 v1, vcc, 0, v1, vcc
	global_store_dword v[0:1], v5, off
	s_branch .LBB0_496

.LBB0_510:
	s_min_u32 s7, s27, 59
	s_add_i32 s7, s7, 4
	s_mul_i32 s7, s3, s7
	s_add_u32 s7, s16, s7
	s_addc_u32 s40, s17, 0
	s_add_u32 s28, s7, s6
	s_addc_u32 s29, s40, 0
	s_add_u32 s34, s7, s14
	s_addc_u32 s35, s40, 0
	s_add_u32 s38, s7, s15
	v_lshl_add_u64 v[52:53], s[28:29], 0, v[112:113]
	s_addc_u32 s39, s40, 0
	global_load_dwordx4 v[52:55], v[52:53], off nt
	v_lshl_add_u64 v[60:61], s[34:35], 0, v[112:113]
	global_load_dwordx4 v[60:63], v[60:61], off nt
	v_lshl_add_u64 v[64:65], s[38:39], 0, v[112:113]
	global_load_dwordx4 v[64:67], v[64:65], off nt
	v_lshl_add_u64 v[68:69], s[28:29], 0, v[114:115]
	global_load_dwordx4 v[68:71], v[68:69], off nt
	v_lshl_add_u64 v[72:73], s[34:35], 0, v[114:115]
	global_load_dwordx4 v[72:75], v[72:73], off nt
	v_lshl_add_u64 v[76:77], s[38:39], 0, v[114:115]
	global_load_dwordx4 v[76:79], v[76:77], off nt
	v_lshl_add_u64 v[80:81], s[28:29], 0, v[116:117]
	global_load_dwordx4 v[80:83], v[80:81], off nt
	v_lshl_add_u64 v[84:85], s[34:35], 0, v[116:117]
	global_load_dwordx4 v[84:87], v[84:85], off nt
	v_lshl_add_u64 v[88:89], s[38:39], 0, v[116:117]
	global_load_dwordx4 v[88:91], v[88:89], off nt
	v_lshl_add_u64 v[92:93], s[28:29], 0, v[118:119]
	global_load_dwordx4 v[92:95], v[92:93], off nt
	v_lshl_add_u64 v[96:97], s[34:35], 0, v[118:119]
	s_add_u32 s28, s7, s26
	global_load_dwordx4 v[96:99], v[96:97], off nt
	v_lshl_add_u64 v[100:101], s[38:39], 0, v[118:119]
	s_addc_u32 s29, s40, 0
	global_load_dwordx4 v[100:103], v[100:101], off nt
	v_lshl_add_u64 v[104:105], s[28:29], 0, v[112:113]
	global_load_dwordx4 v[104:107], v[104:105], off nt
	v_lshl_add_u64 v[108:109], s[28:29], 0, v[120:121]
	global_load_dwordx4 v[108:111], v[108:109], off nt
	s_waitcnt lgkmcnt(0)
	s_barrier
	s_andn2_b64 vcc, exec, s[0:1]
	s_add_i32 s27, s27, 2
	s_cbranch_vccz .LBB0_513

.Lpf_nopub_a1:
	s_add_i32 s0, s0, 3
	s_mul_i32 s0, s3, s0
	s_add_u32 s7, s16, s0
	s_addc_u32 s38, s17, 0
	s_add_u32 s0, s7, s6
	s_addc_u32 s1, s38, 0
	s_add_u32 s28, s7, s14
	s_addc_u32 s29, s38, 0
	s_add_u32 s34, s7, s15
	s_addc_u32 s35, s38, 0
	s_add_u32 s60, s7, s26
	s_addc_u32 s61, s38, 0
	ds_write_b128 v124, v[0:3] offset:62464
	v_lshl_add_u64 v[0:1], s[0:1], 0, v[112:113]
	global_load_dwordx4 v[0:3], v[0:1], off nt
	v_add_u32_e32 v145, v141, v123
	ds_write_b128 v145, v[4:7]
	v_lshl_add_u64 v[4:5], s[28:29], 0, v[112:113]
	global_load_dwordx4 v[4:7], v[4:5], off nt
	v_add_u32_e32 v145, v142, v125
	ds_write_b128 v145, v[8:11]
	v_lshl_add_u64 v[8:9], s[34:35], 0, v[112:113]
	global_load_dwordx4 v[8:11], v[8:9], off nt
	ds_write_b128 v128, v[12:15] offset:62464
	v_lshl_add_u64 v[12:13], s[0:1], 0, v[114:115]
	global_load_dwordx4 v[12:15], v[12:13], off nt
	v_add_u32_e32 v145, v141, v127
	ds_write_b128 v145, v[16:19]
	v_lshl_add_u64 v[16:17], s[28:29], 0, v[114:115]
	global_load_dwordx4 v[16:19], v[16:17], off nt
	v_add_u32_e32 v145, v142, v129
	ds_write_b128 v145, v[20:23]
	v_lshl_add_u64 v[20:21], s[34:35], 0, v[114:115]
	global_load_dwordx4 v[20:23], v[20:21], off nt
	ds_write_b128 v132, v[24:27] offset:62464
	v_lshl_add_u64 v[24:25], s[0:1], 0, v[116:117]
	global_load_dwordx4 v[24:27], v[24:25], off nt
	v_add_u32_e32 v145, v141, v131
	ds_write_b128 v145, v[28:31]
	v_lshl_add_u64 v[28:29], s[28:29], 0, v[116:117]
	global_load_dwordx4 v[28:31], v[28:29], off nt
	v_add_u32_e32 v145, v142, v133
	ds_write_b128 v145, v[32:35]
	v_lshl_add_u64 v[32:33], s[34:35], 0, v[116:117]
	global_load_dwordx4 v[32:35], v[32:33], off nt
	ds_write_b128 v136, v[36:39] offset:62464
	v_lshl_add_u64 v[36:37], s[0:1], 0, v[118:119]
	global_load_dwordx4 v[36:39], v[36:37], off nt
	v_add_u32_e32 v145, v141, v135
	ds_write_b128 v145, v[40:43]
	v_lshl_add_u64 v[40:41], s[28:29], 0, v[118:119]
	global_load_dwordx4 v[40:43], v[40:41], off nt
	v_add_u32_e32 v145, v142, v137
	ds_write_b128 v145, v[44:47]
	v_lshl_add_u64 v[44:45], s[34:35], 0, v[118:119]
	global_load_dwordx4 v[44:47], v[44:45], off nt
	ds_write_b128 v143, v[48:51]
	v_lshl_add_u64 v[48:49], s[60:61], 0, v[112:113]
	global_load_dwordx4 v[48:51], v[48:49], off nt
	ds_write_b128 v144, v[56:59]
	v_lshl_add_u64 v[56:57], s[60:61], 0, v[120:121]
	global_load_dwordx4 v[56:59], v[56:57], off nt
	s_waitcnt lgkmcnt(0)
	s_barrier
	s_waitcnt vmcnt(14)
	s_cmp_eq_u32 s100, 0
	s_cbranch_scc1 .Lpf_nopub_a0
	s_mov_b64 exec, 1
	v_mov_b32_e32 v239, s27
	v_or_b32_e32 v239, 1, v239
	global_store_dword v238, v239, s[98:99]
	s_mov_b64 exec, -1
.Lpf_nopub_a0:
	s_cmp_gt_u32 s27, 61
	s_cselect_b64 s[0:1], -1, 0
	s_and_b64 vcc, exec, s[0:1]
	s_cbranch_vccnz .LBB0_510
	s_min_u32 s7, s27, 59
	s_add_i32 s7, s7, 4
	s_mul_i32 s7, s3, s7
	s_add_u32 s7, s16, s7
	s_addc_u32 s40, s17, 0
	s_add_u32 s28, s7, s6
	s_addc_u32 s29, s40, 0
	s_add_u32 s34, s7, s14
	s_addc_u32 s35, s40, 0
	s_add_u32 s38, s7, s15
	s_addc_u32 s39, s40, 0
	s_add_u32 s60, s7, s26
	s_addc_u32 s61, s40, 0
	ds_write_b128 v124, v[52:55]
	v_lshl_add_u64 v[52:53], s[28:29], 0, v[112:113]
	global_load_dwordx4 v[52:55], v[52:53], off nt
	ds_write_b128 v124, v[60:63] offset:17408
	v_lshl_add_u64 v[60:61], s[34:35], 0, v[112:113]
	global_load_dwordx4 v[60:63], v[60:61], off nt
	ds_write_b128 v126, v[64:67] offset:34816
	v_lshl_add_u64 v[64:65], s[38:39], 0, v[112:113]
	global_load_dwordx4 v[64:67], v[64:65], off nt
	ds_write_b128 v128, v[68:71]
	v_lshl_add_u64 v[68:69], s[28:29], 0, v[114:115]
	global_load_dwordx4 v[68:71], v[68:69], off nt
	ds_write_b128 v128, v[72:75] offset:17408
	v_lshl_add_u64 v[72:73], s[34:35], 0, v[114:115]
	global_load_dwordx4 v[72:75], v[72:73], off nt
	ds_write_b128 v130, v[76:79] offset:34816
	v_lshl_add_u64 v[76:77], s[38:39], 0, v[114:115]
	global_load_dwordx4 v[76:79], v[76:77], off nt
	ds_write_b128 v132, v[80:83]
	v_lshl_add_u64 v[80:81], s[28:29], 0, v[116:117]
	global_load_dwordx4 v[80:83], v[80:81], off nt
	ds_write_b128 v132, v[84:87] offset:17408
	v_lshl_add_u64 v[84:85], s[34:35], 0, v[116:117]
	global_load_dwordx4 v[84:87], v[84:85], off nt
	ds_write_b128 v134, v[88:91] offset:34816
	v_lshl_add_u64 v[88:89], s[38:39], 0, v[116:117]
	global_load_dwordx4 v[88:91], v[88:89], off nt
	ds_write_b128 v136, v[92:95]
	v_lshl_add_u64 v[92:93], s[28:29], 0, v[118:119]
	global_load_dwordx4 v[92:95], v[92:93], off nt
	ds_write_b128 v136, v[96:99] offset:17408
	v_lshl_add_u64 v[96:97], s[34:35], 0, v[118:119]
	global_load_dwordx4 v[96:99], v[96:97], off nt
	ds_write_b128 v138, v[100:103] offset:34816
	v_lshl_add_u64 v[100:101], s[38:39], 0, v[118:119]
	global_load_dwordx4 v[100:103], v[100:101], off nt
	ds_write_b128 v139, v[104:107] offset:53248
	v_lshl_add_u64 v[104:105], s[60:61], 0, v[112:113]
	global_load_dwordx4 v[104:107], v[104:105], off nt
	ds_write_b128 v140, v[108:111] offset:53248
	v_lshl_add_u64 v[108:109], s[60:61], 0, v[120:121]
	global_load_dwordx4 v[108:111], v[108:109], off nt
	s_waitcnt lgkmcnt(0)
	s_barrier
	s_add_i32 s27, s27, 2
	s_branch .LBB0_511

.LBB0_516:
	s_min_u32 s7, s6, 59
	s_add_i32 s7, s7, 4
	s_mul_i32 s7, s3, s7
	s_add_u32 s7, s16, s7
	s_addc_u32 s27, s17, 0
	s_add_u32 s8, s7, s14
	s_addc_u32 s9, s27, 0
	s_add_u32 s12, s7, s15
	s_addc_u32 s13, s27, 0
	v_lshl_add_u64 v[36:37], s[8:9], 0, v[80:81]
	global_load_dwordx4 v[36:39], v[36:37], off nt
	v_lshl_add_u64 v[44:45], s[12:13], 0, v[80:81]
	global_load_dwordx4 v[44:47], v[44:45], off nt
	v_lshl_add_u64 v[48:49], s[8:9], 0, v[82:83]
	global_load_dwordx4 v[48:51], v[48:49], off nt
	v_lshl_add_u64 v[52:53], s[12:13], 0, v[82:83]
	global_load_dwordx4 v[52:55], v[52:53], off nt
	v_lshl_add_u64 v[56:57], s[8:9], 0, v[84:85]
	global_load_dwordx4 v[56:59], v[56:57], off nt
	v_lshl_add_u64 v[60:61], s[12:13], 0, v[84:85]
	global_load_dwordx4 v[60:63], v[60:61], off nt
	v_lshl_add_u64 v[64:65], s[8:9], 0, v[86:87]
	s_add_u32 s8, s7, s26
	global_load_dwordx4 v[64:67], v[64:65], off nt
	v_lshl_add_u64 v[68:69], s[12:13], 0, v[86:87]
	s_addc_u32 s9, s27, 0
	global_load_dwordx4 v[68:71], v[68:69], off nt
	v_lshl_add_u64 v[72:73], s[8:9], 0, v[80:81]
	global_load_dwordx4 v[72:75], v[72:73], off nt
	v_lshl_add_u64 v[76:77], s[8:9], 0, v[88:89]
	global_load_dwordx4 v[76:79], v[76:77], off nt
	s_waitcnt lgkmcnt(0)
	s_barrier
	s_andn2_b64 vcc, exec, s[0:1]
	s_add_i32 s6, s6, 2
	s_cbranch_vccz .LBB0_519

.Lpf_nopub_b1:
	ds_write_b128 v112, v[0:3]
	v_add_u32_e32 v0, v109, v92
	s_add_i32 s0, s0, 3
	ds_write_b128 v0, v[4:7]
	v_add_u32_e32 v0, v108, v94
	s_mul_i32 s0, s3, s0
	ds_write_b128 v0, v[8:11]
	v_add_u32_e32 v0, v109, v96
	s_add_u32 s7, s16, s0
	ds_write_b128 v0, v[12:15]
	v_add_u32_e32 v0, v108, v98
	s_addc_u32 s12, s17, 0
	ds_write_b128 v0, v[16:19]
	v_add_u32_e32 v0, v109, v100
	s_add_u32 s0, s7, s14
	ds_write_b128 v0, v[20:23]
	v_add_u32_e32 v0, v108, v102
	s_addc_u32 s1, s12, 0
	ds_write_b128 v0, v[24:27]
	v_add_u32_e32 v0, v109, v104
	s_add_u32 s8, s7, s15
	ds_write_b128 v0, v[28:31]
	ds_write_b128 v110, v[32:35]
	ds_write_b128 v111, v[40:43]
	s_addc_u32 s9, s12, 0
	v_lshl_add_u64 v[0:1], s[0:1], 0, v[80:81]
	global_load_dwordx4 v[0:3], v[0:1], off nt
	v_lshl_add_u64 v[4:5], s[8:9], 0, v[80:81]
	global_load_dwordx4 v[4:7], v[4:5], off nt
	v_lshl_add_u64 v[8:9], s[0:1], 0, v[82:83]
	global_load_dwordx4 v[8:11], v[8:9], off nt
	v_lshl_add_u64 v[12:13], s[8:9], 0, v[82:83]
	global_load_dwordx4 v[12:15], v[12:13], off nt
	v_lshl_add_u64 v[16:17], s[0:1], 0, v[84:85]
	global_load_dwordx4 v[16:19], v[16:17], off nt
	v_lshl_add_u64 v[20:21], s[8:9], 0, v[84:85]
	global_load_dwordx4 v[20:23], v[20:21], off nt
	v_lshl_add_u64 v[24:25], s[0:1], 0, v[86:87]
	s_add_u32 s0, s7, s26
	global_load_dwordx4 v[24:27], v[24:25], off nt
	v_lshl_add_u64 v[28:29], s[8:9], 0, v[86:87]
	s_addc_u32 s1, s12, 0
	global_load_dwordx4 v[28:31], v[28:29], off nt
	v_lshl_add_u64 v[32:33], s[0:1], 0, v[80:81]
	global_load_dwordx4 v[32:35], v[32:33], off nt
	v_lshl_add_u64 v[40:41], s[0:1], 0, v[88:89]
	global_load_dwordx4 v[40:43], v[40:41], off nt
	s_waitcnt lgkmcnt(0)
	s_barrier
	s_waitcnt vmcnt(10)
	s_cmp_eq_u32 s100, 0
	s_cbranch_scc1 .Lpf_nopub_b0
	s_mov_b64 exec, 1
	v_mov_b32_e32 v239, s6
	v_or_b32_e32 v239, 1, v239
	global_store_dword v238, v239, s[98:99]
	s_mov_b64 exec, -1
